# XCD-last leader issues its acquire invalidate right behind the release write-back (one combined wait) instead of after the write-back wait; otherwise as v061
# baseline (speedup 1.0000x reference)
; DI unsigned xb_add(unsigned* p, unsigned v) { return __hip_atomic_fetch_add(p, v, __ATOMIC_RELAXED, __HIP_MEMORY_SCOPE_AGENT); }
; DI void xcd_barrier(const XcdBarrier& b) {
;     ...
;         if (old + 1u == (gen + 1u) * nloc) {
;             __builtin_amdgcn_fence(__ATOMIC_RELEASE, "agent");
;             asm volatile("s_waitcnt vmcnt(0)" ::: "memory");
;             const unsigned og = xb_add(&bar[XB_TOP], 1u);
.LBB0_188:
	s_andn2_saveexec_b64 s[4:5], s[4:5]
	s_cbranch_execz .LBB0_208
	s_mov_b64 s[6:7], exec
	buffer_wbl2 sc1
	buffer_inv sc1
	s_waitcnt lgkmcnt(0)
	s_waitcnt vmcnt(0)
	v_mbcnt_lo_u32_b32 v1, s6, 0
	v_mbcnt_hi_u32_b32 v1, s7, v1
	v_cmp_eq_u32_e32 vcc, 0, v1
	s_and_saveexec_b64 s[8:9], vcc
	s_cbranch_execz .LBB0_191
	s_bcnt1_i32_b64 s0, s[6:7]
	v_mov_b32_e32 v3, s0
	v_readlane_b32 s0, v253, 45
	v_readlane_b32 s1, v253, 46
	s_nop 4
	global_atomic_add v3, v0, v3, s[0:1] sc0

; DI unsigned xb_add(unsigned* p, unsigned v) { return __hip_atomic_fetch_add(p, v, __ATOMIC_RELAXED, __HIP_MEMORY_SCOPE_AGENT); }
; DI void xcd_barrier(const XcdBarrier& b) {
;     ...
;         if (old + 1u == (gen + 1u) * nloc) {
;             __builtin_amdgcn_fence(__ATOMIC_RELEASE, "agent");
;             asm volatile("s_waitcnt vmcnt(0)" ::: "memory");
;             const unsigned og = xb_add(&bar[XB_TOP], 1u);
.LBB0_373:
	s_andn2_saveexec_b64 s[0:1], s[4:5]
	s_cbranch_execz .LBB0_393
	s_mov_b64 s[4:5], exec
	buffer_wbl2 sc1
	buffer_inv sc1
	s_waitcnt lgkmcnt(0)
	s_waitcnt vmcnt(0)
	v_mbcnt_lo_u32_b32 v1, s4, 0
	v_mbcnt_hi_u32_b32 v1, s5, v1
	v_cmp_eq_u32_e32 vcc, 0, v1
	s_and_saveexec_b64 s[6:7], vcc
	s_cbranch_execz .LBB0_376
	s_bcnt1_i32_b64 s0, s[4:5]
	v_mov_b32_e32 v3, s0
	v_readlane_b32 s0, v253, 45
	v_readlane_b32 s1, v253, 46
	s_nop 4
	global_atomic_add v3, v0, v3, s[0:1] sc0
